# v33 + nontemporal loads of the f32 FFN1 weights in the P0 conversion (read once)
# baseline (speedup 1.0000x reference)
.LBB0_15:
	s_and_b64 s[26:27], s[34:35], exec
	s_cselect_b32 s45, s33, 0
	s_ashr_i32 s19, s18, 31
	s_add_i32 s45, s45, s24
	s_lshl_b64 s[26:27], s[18:19], 2
	v_lshlrev_b32_e32 v0, 3, v128
	s_add_u32 s26, s30, s26
	v_and_b32_e32 v0, 56, v0
	v_ashrrev_i32_e32 v21, 5, v128
	s_addc_u32 s27, s31, s27
	v_lshlrev_b32_e32 v20, 2, v0
	v_add_u32_e32 v0, s18, v21
	global_load_dwordx4 v[8:11], v20, s[26:27] offset:16
	global_load_dwordx4 v[12:15], v20, s[26:27]
	v_mad_i64_i32 v[0:1], s[26:27], v0, s16, 0
	v_lshl_add_u64 v[0:1], v[0:1], 2, s[28:29]
	s_ashr_i32 s21, s20, 31
	v_and_b32_e32 v2, 31, v128
	v_mov_b32_e32 v17, 0
	v_lshl_add_u64 v[0:1], s[20:21], 2, v[0:1]
	v_lshlrev_b32_e32 v16, 2, v2
	s_mov_b32 s41, 0
	v_lshl_add_u64 v[2:3], v[0:1], 0, v[16:17]
	s_lshl_b32 s40, s16, 3
	v_lshl_add_u64 v[4:5], v[2:3], 0, s[40:41]
	v_lshl_add_u64 v[26:27], v[4:5], 0, s[40:41]
	v_lshl_add_u64 v[28:29], v[26:27], 0, s[40:41]
	v_lshl_add_u64 v[30:31], v[28:29], 0, s[40:41]
	v_lshl_add_u64 v[32:33], v[30:31], 0, s[40:41]
	v_lshl_add_u64 v[34:35], v[32:33], 0, s[40:41]
	global_load_dword v46, v[2:3], off nt
	global_load_dword v47, v[4:5], off nt
	global_load_dword v23, v[26:27], off nt
	global_load_dword v24, v[28:29], off nt
	global_load_dword v6, v[30:31], off nt
	global_load_dword v19, v[32:33], off nt
	global_load_dword v0, v[34:35], off nt
	v_lshl_add_u64 v[2:3], v[34:35], 0, s[40:41]
	global_load_dword v51, v[2:3], off nt
	v_lshl_add_u64 v[2:3], v[2:3], 0, s[40:41]
	global_load_dword v52, v[2:3], off nt
	v_lshl_add_u64 v[2:3], v[2:3], 0, s[40:41]
	global_load_dword v53, v[2:3], off nt
	v_lshl_add_u64 v[2:3], v[2:3], 0, s[40:41]
	global_load_dword v25, v[2:3], off nt
	v_lshl_add_u64 v[2:3], v[2:3], 0, s[40:41]
	global_load_dword v54, v[2:3], off nt
	v_lshl_add_u64 v[2:3], v[2:3], 0, s[40:41]
	global_load_dword v31, v[2:3], off nt
	v_lshl_add_u64 v[2:3], v[2:3], 0, s[40:41]
	global_load_dword v55, v[2:3], off nt
	v_lshl_add_u64 v[2:3], v[2:3], 0, s[40:41]
	global_load_dword v26, v[2:3], off nt
	v_lshl_add_u64 v[2:3], v[2:3], 0, s[40:41]
	global_load_dword v57, v[2:3], off nt
	v_lshl_add_u64 v[2:3], v[2:3], 0, s[40:41]
	global_load_dword v27, v[2:3], off nt
	v_lshl_add_u64 v[2:3], v[2:3], 0, s[40:41]
	global_load_dword v58, v[2:3], off nt
	v_lshl_add_u64 v[2:3], v[2:3], 0, s[40:41]
	global_load_dword v7, v[2:3], off nt
	v_lshl_add_u64 v[2:3], v[2:3], 0, s[40:41]
	global_load_dword v32, v[2:3], off nt
	v_lshl_add_u64 v[2:3], v[2:3], 0, s[40:41]
	global_load_dword v18, v[2:3], off nt
	v_lshl_add_u64 v[2:3], v[2:3], 0, s[40:41]
	v_lshl_add_u64 v[4:5], v[2:3], 0, s[40:41]
	global_load_dword v33, v[2:3], off nt
	s_cmp_lt_i32 s45, 0x10200
	global_load_dword v2, v[4:5], off nt
	v_lshl_add_u64 v[4:5], v[4:5], 0, s[40:41]
	global_load_dword v28, v[4:5], off nt
	v_lshl_add_u64 v[4:5], v[4:5], 0, s[40:41]
	global_load_dword v3, v[4:5], off nt
	v_lshl_add_u64 v[4:5], v[4:5], 0, s[40:41]
	global_load_dword v29, v[4:5], off nt
	v_lshl_add_u64 v[4:5], v[4:5], 0, s[40:41]
	v_lshl_add_u64 v[34:35], v[4:5], 0, s[40:41]
	global_load_dword v1, v[4:5], off nt
	s_cselect_b64 s[38:39], -1, 0
	global_load_dword v4, v[34:35], off nt
	v_lshl_add_u64 v[34:35], v[34:35], 0, s[40:41]
	global_load_dword v5, v[34:35], off nt
	v_lshl_add_u64 v[34:35], v[34:35], 0, s[40:41]
	v_lshl_add_u64 v[36:37], v[34:35], 0, s[40:41]
	global_load_dword v30, v[34:35], off nt
	s_cmp_gt_i32 s45, 0x101ff
	global_load_dword v34, v[36:37], off nt
	v_lshl_add_u64 v[36:37], v[36:37], 0, s[40:41]
	global_load_dword v67, v[36:37], off nt
	s_mov_b32 s44, s47
	s_mov_b32 s26, s46
	s_mov_b64 s[34:35], s[36:37]
	s_cbranch_scc1 .LBB0_21
	s_cmp_gt_i32 s45, 0xabff
	s_cbranch_scc0 .LBB0_19
	s_add_i32 s0, s45, 0xffff5400
	s_lshr_b32 s16, s0, 13
	s_mov_b32 s17, 0
	s_lshl_b64 s[16:17], s[16:17], 25
	s_add_u32 s34, s23, s16
	s_addc_u32 s35, s25, s17
	s_lshr_b32 s0, s0, 1
	s_lshl_b32 s1, s45, 5
	s_and_b32 s18, s0, 0x7fffffc0
	s_and_b32 s20, s1, 0xfe0
	s_and_b32 s44, s0, 0xfc0
	s_cbranch_execz .LBB0_20
	s_movk_i32 s16, 0x1000
	s_getpc_b64 s[30:31]
	s_add_u32 s30, s30, _ZL4ONES@rel32@lo+4
	s_addc_u32 s31, s31, _ZL4ONES@rel32@hi+12
	s_mov_b64 s[28:29], s[10:11]
	s_mov_b32 s26, s20
	s_branch .LBB0_21

.LBB0_21:
	s_ashr_i32 s19, s18, 31
	s_lshl_b64 s[42:43], s[18:19], 2
	v_add_u32_e32 v22, s18, v21
	s_add_u32 s42, s30, s42
	v_mad_i64_i32 v[36:37], s[48:49], v22, s16, 0
	s_addc_u32 s43, s31, s43
	v_lshl_add_u64 v[36:37], v[36:37], 2, s[28:29]
	s_ashr_i32 s21, s20, 31
	v_lshl_add_u64 v[36:37], s[20:21], 2, v[36:37]
	v_lshl_add_u64 v[36:37], v[36:37], 0, v[16:17]
	s_lshl_b32 s40, s16, 3
	v_lshl_add_u64 v[38:39], v[36:37], 0, s[40:41]
	v_lshl_add_u64 v[40:41], v[38:39], 0, s[40:41]
	v_lshl_add_u64 v[42:43], v[40:41], 0, s[40:41]
	v_lshl_add_u64 v[44:45], v[42:43], 0, s[40:41]
	v_lshl_add_u64 v[48:49], v[44:45], 0, s[40:41]
	v_lshl_add_u64 v[60:61], v[48:49], 0, s[40:41]
	global_load_dword v35, v[36:37], off nt
	s_nop 0
	global_load_dword v36, v[38:39], off nt
	global_load_dword v37, v[40:41], off nt
	s_nop 0
	global_load_dword v39, v[42:43], off nt
	global_load_dword v40, v[44:45], off nt
	global_load_dword v41, v[48:49], off nt
	global_load_dword v38, v[60:61], off nt
	v_lshl_add_u64 v[44:45], v[60:61], 0, s[40:41]
	global_load_dword v42, v[44:45], off nt
	v_lshl_add_u64 v[44:45], v[44:45], 0, s[40:41]
	v_lshl_add_u64 v[48:49], v[44:45], 0, s[40:41]
	s_movk_i32 s0, 0x84
	global_load_dword v43, v[44:45], off nt
	v_mul_lo_u32 v17, v21, s0
	global_load_dword v44, v[48:49], off nt
	v_lshl_add_u64 v[48:49], v[48:49], 0, s[40:41]
	global_load_dword v45, v[48:49], off nt
	v_lshl_add_u64 v[48:49], v[48:49], 0, s[40:41]
	v_add3_u32 v22, s82, v16, v17
	s_waitcnt vmcnt(41)
	ds_write2_b32 v22, v46, v47 offset1:66
	global_load_dword v46, v[48:49], off nt
	v_lshl_add_u64 v[48:49], v[48:49], 0, s[40:41]
	v_lshl_add_u64 v[60:61], v[48:49], 0, s[40:41]
	global_load_dword v47, v[48:49], off nt
	s_waitcnt vmcnt(41)
	ds_write2_b32 v22, v23, v24 offset0:132 offset1:198
	global_load_dword v48, v[60:61], off nt
	v_lshl_add_u64 v[60:61], v[60:61], 0, s[40:41]
	global_load_dword v49, v[60:61], off nt
	v_lshl_add_u64 v[60:61], v[60:61], 0, s[40:41]
	v_add_u32_e32 v23, 0x400, v22
	global_load_dword v50, v[60:61], off nt
	v_lshl_add_u64 v[60:61], v[60:61], 0, s[40:41]
	s_waitcnt vmcnt(40)
	ds_write2_b32 v23, v0, v51 offset0:140 offset1:206
	global_load_dword v51, v[60:61], off nt
	v_lshl_add_u64 v[60:61], v[60:61], 0, s[40:41]
	v_add_u32_e32 v24, 0x800, v22
	s_waitcnt vmcnt(39)
	ds_write2_b32 v24, v52, v53 offset0:16 offset1:82
	global_load_dword v52, v[60:61], off nt
	v_lshl_add_u64 v[60:61], v[60:61], 0, s[40:41]
	global_load_dword v53, v[60:61], off nt
	v_lshl_add_u64 v[60:61], v[60:61], 0, s[40:41]
	s_waitcnt vmcnt(39)
	ds_write2_b32 v24, v25, v54 offset0:148 offset1:214
	global_load_dword v54, v[60:61], off nt
	v_lshl_add_u64 v[60:61], v[60:61], 0, s[40:41]
	v_add_u32_e32 v25, 0xc00, v22
	s_waitcnt vmcnt(38)
	ds_write2_b32 v25, v31, v55 offset0:24 offset1:90
	global_load_dword v55, v[60:61], off nt
	v_lshl_add_u64 v[60:61], v[60:61], 0, s[40:41]
	global_load_dword v56, v[60:61], off nt
	v_lshl_add_u64 v[60:61], v[60:61], 0, s[40:41]
	s_waitcnt vmcnt(38)
	ds_write2_b32 v25, v26, v57 offset0:156 offset1:222
	global_load_dword v57, v[60:61], off nt
	v_lshl_add_u64 v[60:61], v[60:61], 0, s[40:41]
	v_add_u32_e32 v26, 0x1000, v22
	s_waitcnt vmcnt(37)
	ds_write2_b32 v26, v27, v58 offset0:32 offset1:98
	global_load_dword v58, v[60:61], off nt
	v_lshl_add_u64 v[60:61], v[60:61], 0, s[40:41]
	v_lshl_add_u64 v[62:63], v[60:61], 0, s[40:41]
	ds_write2_b32 v23, v6, v19 offset0:8 offset1:74
	s_waitcnt vmcnt(36)
	ds_write2_b32 v26, v7, v32 offset0:164 offset1:230
	v_lshl_add_u64 v[6:7], v[62:63], 0, s[40:41]
	global_load_dword v59, v[60:61], off nt
	v_add_u32_e32 v27, 0x1400, v22
	global_load_dword v61, v[6:7], off nt
	v_lshl_add_u64 v[6:7], v[6:7], 0, s[40:41]
	global_load_dword v60, v[62:63], off nt
	s_waitcnt vmcnt(35)
	ds_write2_b32 v27, v2, v28 offset0:172 offset1:238
	global_load_dword v62, v[6:7], off nt
	v_lshl_add_u64 v[6:7], v[6:7], 0, s[40:41]
	global_load_dword v63, v[6:7], off nt
	v_lshl_add_u64 v[6:7], v[6:7], 0, s[40:41]
	v_add_u32_e32 v28, 0x1800, v22
	s_waitcnt vmcnt(35)
	ds_write2_b32 v28, v3, v29 offset0:48 offset1:114
	v_lshl_add_u64 v[2:3], v[6:7], 0, s[40:41]
	global_load_dword v65, v[2:3], off nt
	v_lshl_add_u64 v[2:3], v[2:3], 0, s[40:41]
	v_add_u32_e32 v29, 0x1c00, v22
	ds_write2_b32 v27, v18, v33 offset0:40 offset1:106
	global_load_dword v64, v[6:7], off nt
	global_load_dword v66, v[2:3], off nt
	s_waitcnt vmcnt(36)
	ds_write2_b32 v28, v1, v4 offset0:180 offset1:246
	s_waitcnt vmcnt(34)
	ds_write2_b32 v29, v5, v30 offset0:56 offset1:122
	s_waitcnt vmcnt(32)
	ds_write2_b32 v29, v34, v67 offset0:188 offset1:254
	v_and_b32_e32 v17, 7, v128
	v_ashrrev_i32_e32 v30, 3, v128
	v_mul_u32_u24_e32 v0, 0x420, v17
	v_lshlrev_b32_e32 v1, 2, v30
	v_add3_u32 v31, s82, v0, v1
	global_load_dwordx4 v[0:3], v20, s[42:43] offset:16
	global_load_dwordx4 v[4:7], v20, s[42:43]
	s_waitcnt lgkmcnt(0)
	ds_read2_b32 v[32:33], v31 offset0:33 offset1:41
	ds_read2_b32 v[72:73], v31 offset0:99 offset1:107
	ds_read2_b32 v[74:75], v31 offset0:165 offset1:173
	ds_read2_b32 v[76:77], v31 offset0:231 offset1:239
	v_mov_b32_e32 v19, v14
	v_mov_b32_e32 v14, v13
	s_waitcnt lgkmcnt(3)
	v_mov_b32_e32 v68, v32
	s_waitcnt lgkmcnt(2)
	v_mov_b32_e32 v69, v72
	v_pk_mul_f32 v[68:69], v[14:15], v[68:69]
	s_movk_i32 s27, 0x7fff
	v_bfe_u32 v13, v68, 16, 1
	v_bfe_u32 v18, v69, 16, 1
	ds_read2_b32 v[80:81], v31 offset0:132 offset1:140
	ds_read2_b32 v[82:83], v31 offset0:198 offset1:206
	v_add3_u32 v13, v68, v13, s27
	v_add3_u32 v32, v69, v18, s27
	v_mov_b32_e32 v79, v10
	v_mov_b32_e32 v10, v9
	s_waitcnt lgkmcnt(3)
	v_mov_b32_e32 v68, v74
	s_waitcnt lgkmcnt(2)
	v_mov_b32_e32 v69, v76
	v_pk_mul_f32 v[68:69], v[10:11], v[68:69]
	ds_read2_b32 v[84:85], v31 offset1:8
	ds_read2_b32 v[86:87], v31 offset0:66 offset1:74
	v_bfe_u32 v9, v68, 16, 1
	v_add3_u32 v34, v68, v9, s27
	v_bfe_u32 v9, v69, 16, 1
	v_add3_u32 v67, v69, v9, s27
	v_mov_b32_e32 v78, v8
	s_waitcnt lgkmcnt(3)
	v_mov_b32_e32 v8, v80
	s_waitcnt lgkmcnt(2)
	v_mov_b32_e32 v9, v82
	v_pk_mul_f32 v[8:9], v[78:79], v[8:9]
	s_mov_b32 s42, 0xffff0000
	v_bfe_u32 v18, v9, 16, 1
	v_add3_u32 v68, v9, v18, s27
	v_bfe_u32 v9, v8, 16, 1
	v_add3_u32 v69, v8, v9, s27
	v_mov_b32_e32 v18, v12
	s_waitcnt lgkmcnt(1)
	v_mov_b32_e32 v8, v84
	s_waitcnt lgkmcnt(0)
	v_mov_b32_e32 v9, v86
	v_pk_mul_f32 v[8:9], v[18:19], v[8:9]
	v_lshrrev_b32_e32 v68, 16, v68
	v_bfe_u32 v12, v9, 16, 1
	v_add3_u32 v9, v9, v12, s27
	v_bfe_u32 v12, v8, 16, 1
	v_add3_u32 v8, v8, v12, s27
	v_lshrrev_b32_e32 v9, 16, v9
	v_lshrrev_b32_e32 v8, 16, v8
	v_lshrrev_b32_e32 v12, 16, v69
	v_and_or_b32 v71, v67, s42, v68
	v_and_or_b32 v69, v32, s42, v9
	v_and_or_b32 v68, v13, s42, v8
	v_lshlrev_b32_e32 v32, 3, v17
	v_add_u32_e32 v8, s46, v30
	v_and_or_b32 v70, v34, s42, v12
	v_ashrrev_i32_e32 v9, 31, v8
	v_or_b32_e32 v12, s47, v32
	v_lshlrev_b64 v[8:9], 13, v[8:9]
	v_ashrrev_i32_e32 v13, 31, v12
	v_lshl_add_u64 v[8:9], s[36:37], 0, v[8:9]
	v_lshlrev_b64 v[12:13], 1, v[12:13]
	v_lshl_add_u64 v[8:9], v[8:9], 0, v[12:13]
	v_mov_b32_e32 v72, v33
	global_store_dwordx4 v[8:9], v[68:71], off
	v_pk_mul_f32 v[8:9], v[14:15], v[72:73]
	v_mov_b32_e32 v76, v75
	v_bfe_u32 v17, v8, 16, 1
	v_add3_u32 v17, v8, v17, s27
	v_bfe_u32 v8, v9, 16, 1
	v_add3_u32 v33, v9, v8, s27
	v_pk_mul_f32 v[8:9], v[10:11], v[76:77]
	v_mov_b32_e32 v82, v81
	v_bfe_u32 v34, v8, 16, 1
	v_add3_u32 v34, v8, v34, s27
	v_bfe_u32 v8, v9, 16, 1
	v_add3_u32 v67, v9, v8, s27
	v_pk_mul_f32 v[8:9], v[78:79], v[82:83]
	v_mov_b32_e32 v86, v85
	v_bfe_u32 v68, v9, 16, 1
	v_add3_u32 v68, v9, v68, s27
	v_bfe_u32 v9, v8, 16, 1
	v_add3_u32 v69, v8, v9, s27
	v_pk_mul_f32 v[8:9], v[18:19], v[86:87]
	v_lshrrev_b32_e32 v69, 16, v69
	v_bfe_u32 v70, v9, 16, 1
	v_add3_u32 v9, v9, v70, s27
	v_bfe_u32 v70, v8, 16, 1
	v_add3_u32 v8, v8, v70, s27
	v_lshrrev_b32_e32 v9, 16, v9
	v_lshrrev_b32_e32 v68, 16, v68
	v_and_or_b32 v70, v34, s42, v69
	v_and_or_b32 v69, v33, s42, v9
	v_lshrrev_b32_e32 v8, 16, v8
	v_add_u32_e32 v33, 8, v30
	v_and_or_b32 v71, v67, s42, v68
	v_and_or_b32 v68, v17, s42, v8
	v_add_u32_e32 v8, s46, v33
	v_ashrrev_i32_e32 v9, 31, v8
	v_lshlrev_b64 v[8:9], 13, v[8:9]
	ds_read2_b32 v[72:73], v31 offset0:49 offset1:57
	ds_read2_b32 v[74:75], v31 offset0:115 offset1:123
	v_lshl_add_u64 v[8:9], s[36:37], 0, v[8:9]
	v_lshl_add_u64 v[8:9], v[8:9], 0, v[12:13]
	global_store_dwordx4 v[8:9], v[68:71], off
	ds_read2_b32 v[76:77], v31 offset0:181 offset1:189
	ds_read2_b32 v[80:81], v31 offset0:247 offset1:255
	s_waitcnt lgkmcnt(3)
	v_mov_b32_e32 v8, v72
	s_waitcnt lgkmcnt(2)
	v_mov_b32_e32 v9, v74
	v_pk_mul_f32 v[8:9], v[14:15], v[8:9]
	ds_read2_b32 v[82:83], v31 offset0:148 offset1:156
	ds_read2_b32 v[84:85], v31 offset0:214 offset1:222
	v_bfe_u32 v17, v8, 16, 1
	v_add3_u32 v17, v8, v17, s27
	v_bfe_u32 v8, v9, 16, 1
	v_add3_u32 v34, v9, v8, s27
	s_waitcnt lgkmcnt(3)
	v_mov_b32_e32 v8, v76
	s_waitcnt lgkmcnt(2)
	v_mov_b32_e32 v9, v80
	v_pk_mul_f32 v[8:9], v[10:11], v[8:9]
	ds_read2_b32 v[86:87], v31 offset0:16 offset1:24
	ds_read2_b32 v[88:89], v31 offset0:82 offset1:90
	v_bfe_u32 v67, v8, 16, 1
	v_add3_u32 v67, v8, v67, s27
	v_bfe_u32 v8, v9, 16, 1
	v_add3_u32 v68, v9, v8, s27
	s_waitcnt lgkmcnt(3)
	v_mov_b32_e32 v8, v82
	s_waitcnt lgkmcnt(2)
	v_mov_b32_e32 v9, v84
	v_pk_mul_f32 v[8:9], v[78:79], v[8:9]
	v_mov_b32_e32 v74, v73
	v_bfe_u32 v69, v9, 16, 1
	v_add3_u32 v69, v9, v69, s27
	v_bfe_u32 v9, v8, 16, 1
	v_add3_u32 v70, v8, v9, s27
	s_waitcnt lgkmcnt(1)
	v_mov_b32_e32 v8, v86
	s_waitcnt lgkmcnt(0)
	v_mov_b32_e32 v9, v88
	v_pk_mul_f32 v[8:9], v[18:19], v[8:9]
	v_lshrrev_b32_e32 v69, 16, v69
	v_bfe_u32 v71, v9, 16, 1
	v_add3_u32 v9, v9, v71, s27
	v_bfe_u32 v71, v8, 16, 1
	v_add3_u32 v8, v8, v71, s27
	v_lshrrev_b32_e32 v9, 16, v9
	v_and_or_b32 v71, v68, s42, v69
	v_and_or_b32 v69, v34, s42, v9
	v_lshrrev_b32_e32 v8, 16, v8
	v_add_u32_e32 v34, 16, v30
	v_and_or_b32 v68, v17, s42, v8
	v_add_u32_e32 v8, s46, v34
	v_ashrrev_i32_e32 v9, 31, v8
	v_lshlrev_b64 v[8:9], 13, v[8:9]
	v_lshrrev_b32_e32 v70, 16, v70
	v_lshl_add_u64 v[8:9], s[36:37], 0, v[8:9]
	v_and_or_b32 v70, v67, s42, v70
	v_lshl_add_u64 v[8:9], v[8:9], 0, v[12:13]
	global_store_dwordx4 v[8:9], v[68:71], off
	v_pk_mul_f32 v[8:9], v[14:15], v[74:75]
	v_mov_b32_e32 v80, v77
	v_bfe_u32 v17, v8, 16, 1
	v_pk_mul_f32 v[10:11], v[10:11], v[80:81]
	v_add3_u32 v8, v8, v17, s27
	v_bfe_u32 v17, v9, 16, 1
	v_mov_b32_e32 v88, v87
	v_mov_b32_e32 v84, v83
	v_add3_u32 v9, v9, v17, s27
	v_bfe_u32 v17, v10, 16, 1
	v_pk_mul_f32 v[14:15], v[18:19], v[88:89]
	v_pk_mul_f32 v[18:19], v[78:79], v[84:85]
	v_add3_u32 v10, v10, v17, s27
	v_bfe_u32 v17, v11, 16, 1
	v_add3_u32 v11, v11, v17, s27
	v_bfe_u32 v17, v19, 16, 1
	v_add3_u32 v17, v19, v17, s27
	v_bfe_u32 v19, v18, 16, 1
	v_add3_u32 v18, v18, v19, s27
	v_bfe_u32 v19, v15, 16, 1
	v_add3_u32 v15, v15, v19, s27
	v_bfe_u32 v19, v14, 16, 1
	v_add3_u32 v14, v14, v19, s27
	v_lshrrev_b32_e32 v18, 16, v18
	v_and_or_b32 v10, v10, s42, v18
	v_lshrrev_b32_e32 v14, 16, v14
	v_add_u32_e32 v18, 24, v30
	v_lshrrev_b32_e32 v15, 16, v15
	v_and_or_b32 v8, v8, s42, v14
	v_add_u32_e32 v14, s46, v18
	v_and_or_b32 v9, v9, s42, v15
	v_ashrrev_i32_e32 v15, 31, v14
	v_lshlrev_b64 v[14:15], 13, v[14:15]
	v_lshrrev_b32_e32 v17, 16, v17
	v_lshl_add_u64 v[14:15], s[36:37], 0, v[14:15]
	v_and_or_b32 v11, v11, s42, v17
	v_lshl_add_u64 v[12:13], v[14:15], 0, v[12:13]
	global_store_dwordx4 v[12:13], v[8:11], off
	s_waitcnt lgkmcnt(0)
	s_andn2_b64 vcc, exec, s[38:39]
	s_cbranch_vccnz .LBB0_38
	s_and_b64 s[36:37], s[38:39], exec
	s_cselect_b32 s0, s33, 0
	s_mov_b32 s17, 0
	s_add_i32 s43, s0, s45
	v_mov_b32_e32 v17, 0
	s_branch .LBB0_26

.LBB0_24:
	s_and_b64 s[40:41], s[40:41], exec
	s_cselect_b32 s0, s33, 0
	s_add_i32 s43, s0, s19
	s_ashr_i32 s19, s18, 31
	s_lshl_b64 s[40:41], s[18:19], 2
	s_add_u32 s40, s30, s40
	s_addc_u32 s41, s31, s41
	v_add_u32_e32 v35, s18, v21
	global_load_dwordx4 v[0:3], v20, s[40:41] offset:16
	global_load_dwordx4 v[4:7], v20, s[40:41]
	v_mad_u64_u32 v[36:37], s[40:41], v35, s16, 0
	v_ashrrev_i32_e32 v39, 31, v35
	v_mov_b32_e32 v38, v37
	v_mad_u64_u32 v[38:39], s[40:41], v39, s16, v[38:39]
	v_mov_b32_e32 v37, v38
	v_lshl_add_u64 v[36:37], v[36:37], 2, s[28:29]
	s_ashr_i32 s21, s20, 31
	v_lshl_add_u64 v[36:37], s[20:21], 2, v[36:37]
	v_lshl_add_u64 v[36:37], v[36:37], 0, v[16:17]
	s_lshl_b64 s[40:41], s[16:17], 3
	v_lshl_add_u64 v[38:39], v[36:37], 0, s[40:41]
	v_lshl_add_u64 v[40:41], v[38:39], 0, s[40:41]
	v_lshl_add_u64 v[42:43], v[40:41], 0, s[40:41]
	v_lshl_add_u64 v[44:45], v[42:43], 0, s[40:41]
	v_lshl_add_u64 v[46:47], v[44:45], 0, s[40:41]
	v_lshl_add_u64 v[48:49], v[46:47], 0, s[40:41]
	global_load_dword v35, v[36:37], off nt
	s_nop 0
	global_load_dword v36, v[38:39], off nt
	global_load_dword v37, v[40:41], off nt
	s_nop 0
	global_load_dword v39, v[42:43], off nt
	global_load_dword v40, v[44:45], off nt
	global_load_dword v41, v[46:47], off nt
	global_load_dword v38, v[48:49], off nt
	v_lshl_add_u64 v[44:45], v[48:49], 0, s[40:41]
	global_load_dword v42, v[44:45], off nt
	v_lshl_add_u64 v[44:45], v[44:45], 0, s[40:41]
	v_lshl_add_u64 v[46:47], v[44:45], 0, s[40:41]
	global_load_dword v43, v[44:45], off nt
	s_nop 0
	global_load_dword v44, v[46:47], off nt
	v_lshl_add_u64 v[46:47], v[46:47], 0, s[40:41]
	v_lshl_add_u64 v[48:49], v[46:47], 0, s[40:41]
	global_load_dword v45, v[46:47], off nt
	s_nop 0
	global_load_dword v46, v[48:49], off nt
	v_lshl_add_u64 v[48:49], v[48:49], 0, s[40:41]
	v_lshl_add_u64 v[50:51], v[48:49], 0, s[40:41]
	global_load_dword v47, v[48:49], off nt
	s_nop 0
	global_load_dword v48, v[50:51], off nt
	v_lshl_add_u64 v[50:51], v[50:51], 0, s[40:41]
	v_lshl_add_u64 v[52:53], v[50:51], 0, s[40:41]
	global_load_dword v49, v[50:51], off nt
	s_nop 0
	global_load_dword v50, v[52:53], off nt
	v_lshl_add_u64 v[52:53], v[52:53], 0, s[40:41]
	v_lshl_add_u64 v[54:55], v[52:53], 0, s[40:41]
	global_load_dword v51, v[52:53], off nt
	s_nop 0
	global_load_dword v52, v[54:55], off nt
	v_lshl_add_u64 v[54:55], v[54:55], 0, s[40:41]
	v_lshl_add_u64 v[56:57], v[54:55], 0, s[40:41]
	global_load_dword v53, v[54:55], off nt
	s_nop 0
	global_load_dword v54, v[56:57], off nt
	v_lshl_add_u64 v[56:57], v[56:57], 0, s[40:41]
	v_lshl_add_u64 v[58:59], v[56:57], 0, s[40:41]
	global_load_dword v55, v[56:57], off nt
	s_nop 0
	global_load_dword v56, v[58:59], off nt
	v_lshl_add_u64 v[58:59], v[58:59], 0, s[40:41]
	v_lshl_add_u64 v[60:61], v[58:59], 0, s[40:41]
	global_load_dword v57, v[58:59], off nt
	s_nop 0
	global_load_dword v58, v[60:61], off nt
	v_lshl_add_u64 v[60:61], v[60:61], 0, s[40:41]
	v_lshl_add_u64 v[62:63], v[60:61], 0, s[40:41]
	global_load_dword v59, v[60:61], off nt
	s_nop 0
	global_load_dword v60, v[62:63], off nt
	v_lshl_add_u64 v[62:63], v[62:63], 0, s[40:41]
	v_lshl_add_u64 v[64:65], v[62:63], 0, s[40:41]
	global_load_dword v61, v[62:63], off nt
	s_nop 0
	global_load_dword v62, v[64:65], off nt
	v_lshl_add_u64 v[64:65], v[64:65], 0, s[40:41]
	v_lshl_add_u64 v[98:99], v[64:65], 0, s[40:41]
	global_load_dword v63, v[64:65], off nt
	s_nop 0
	global_load_dword v64, v[98:99], off nt
	v_lshl_add_u64 v[98:99], v[98:99], 0, s[40:41]
	global_load_dword v65, v[98:99], off nt
	v_lshl_add_u64 v[98:99], v[98:99], 0, s[40:41]
	global_load_dword v66, v[98:99], off nt
	s_waitcnt vmcnt(62)
	ds_write2_b32 v22, v19, v67 offset1:66
	ds_write2_b32 v22, v68, v69 offset0:132 offset1:198
	ds_write2_b32 v23, v70, v71 offset0:8 offset1:74
	ds_write2_b32 v23, v72, v73 offset0:140 offset1:206
	ds_write2_b32 v24, v74, v75 offset0:16 offset1:82
	s_waitcnt vmcnt(60)
	ds_write2_b32 v24, v76, v77 offset0:148 offset1:214
	s_waitcnt vmcnt(58)
	ds_write2_b32 v25, v78, v79 offset0:24 offset1:90
	s_waitcnt vmcnt(56)
	ds_write2_b32 v25, v80, v81 offset0:156 offset1:222
	s_waitcnt vmcnt(54)
	ds_write2_b32 v26, v82, v83 offset0:32 offset1:98
	s_waitcnt vmcnt(52)
	ds_write2_b32 v26, v84, v85 offset0:164 offset1:230
	s_waitcnt vmcnt(50)
	ds_write2_b32 v27, v86, v87 offset0:40 offset1:106
	s_waitcnt vmcnt(48)
	ds_write2_b32 v27, v88, v89 offset0:172 offset1:238
	s_waitcnt vmcnt(46)
	ds_write2_b32 v28, v90, v91 offset0:48 offset1:114
	s_waitcnt vmcnt(44)
	ds_write2_b32 v28, v92, v93 offset0:180 offset1:246
	s_waitcnt vmcnt(42)
	ds_write2_b32 v29, v94, v95 offset0:56 offset1:122
	s_waitcnt vmcnt(40)
	ds_write2_b32 v29, v96, v97 offset0:188 offset1:254
	s_waitcnt lgkmcnt(0)
	ds_read2_b32 v[72:73], v31 offset0:33 offset1:41
	ds_read2_b32 v[74:75], v31 offset1:8
	ds_read2_b32 v[76:77], v31 offset0:66 offset1:74
	ds_read2_b32 v[78:79], v31 offset0:99 offset1:107
	ds_read2_b32 v[82:83], v31 offset0:132 offset1:140
	ds_read2_b32 v[84:85], v31 offset0:165 offset1:173
	ds_read2_b32 v[86:87], v31 offset0:198 offset1:206
	ds_read2_b32 v[88:89], v31 offset0:231 offset1:239
	s_waitcnt vmcnt(38)
	v_mov_b32_e32 v80, v12
	v_mov_b32_e32 v81, v14
	v_mov_b32_e32 v14, v13
	s_waitcnt lgkmcnt(7)
	v_mov_b32_e32 v12, v72
	s_waitcnt lgkmcnt(4)
	v_mov_b32_e32 v13, v78
	v_pk_mul_f32 v[12:13], v[14:15], v[12:13]
	v_mov_b32_e32 v90, v8
	v_mov_b32_e32 v91, v10
	s_waitcnt lgkmcnt(3)
	v_mov_b32_e32 v70, v82
	s_waitcnt lgkmcnt(1)
	v_mov_b32_e32 v71, v86
	v_mov_b32_e32 v10, v9
	v_mov_b32_e32 v8, v84
	s_waitcnt lgkmcnt(0)
	v_mov_b32_e32 v9, v88
	v_mov_b32_e32 v68, v74
	v_mov_b32_e32 v69, v76
	v_pk_mul_f32 v[70:71], v[90:91], v[70:71]
	v_pk_mul_f32 v[8:9], v[10:11], v[8:9]
	v_bfe_u32 v72, v13, 16, 1
	v_pk_mul_f32 v[68:69], v[80:81], v[68:69]
	v_bfe_u32 v19, v9, 16, 1
	v_bfe_u32 v74, v12, 16, 1
	v_add3_u32 v13, v13, v72, s27
	v_bfe_u32 v72, v70, 16, 1
	v_bfe_u32 v67, v8, 16, 1
	v_add3_u32 v12, v12, v74, s27
	v_add3_u32 v9, v9, v19, s27
	v_bfe_u32 v19, v68, 16, 1
	v_bfe_u32 v74, v71, 16, 1
	v_add3_u32 v70, v70, v72, s27
	v_add3_u32 v8, v8, v67, s27
	v_bfe_u32 v67, v69, 16, 1
	v_add3_u32 v71, v71, v74, s27
	v_add3_u32 v19, v68, v19, s27
	v_lshrrev_b32_e32 v68, 16, v70
	v_add3_u32 v67, v69, v67, s27
	v_lshrrev_b32_e32 v19, 16, v19
	v_lshrrev_b32_e32 v69, 16, v71
	v_and_or_b32 v70, v8, s42, v68
	v_add_u32_e32 v8, s45, v30
	v_lshrrev_b32_e32 v67, 16, v67
	v_and_or_b32 v71, v9, s42, v69
	v_and_or_b32 v68, v12, s42, v19
	v_ashrrev_i32_e32 v9, 31, v8
	v_add_u32_e32 v12, s46, v32
	v_and_or_b32 v69, v13, s42, v67
	v_lshlrev_b64 v[8:9], 13, v[8:9]
	v_ashrrev_i32_e32 v13, 31, v12
	v_lshl_add_u64 v[8:9], s[36:37], 0, v[8:9]
	v_lshlrev_b64 v[12:13], 1, v[12:13]
	v_mov_b32_e32 v88, v85
	v_lshl_add_u64 v[8:9], v[8:9], 0, v[12:13]
	v_mov_b32_e32 v76, v75
	v_mov_b32_e32 v78, v73
	v_pk_mul_f32 v[72:73], v[10:11], v[88:89]
	global_store_dwordx4 v[8:9], v[68:71], off
	v_pk_mul_f32 v[8:9], v[80:81], v[76:77]
	v_bfe_u32 v67, v72, 16, 1
	v_pk_mul_f32 v[68:69], v[14:15], v[78:79]
	v_bfe_u32 v19, v73, 16, 1
	v_add3_u32 v67, v72, v67, s27
	v_bfe_u32 v72, v8, 16, 1
	v_bfe_u32 v75, v68, 16, 1
	v_add3_u32 v19, v73, v19, s27
	v_bfe_u32 v73, v9, 16, 1
	v_add3_u32 v8, v8, v72, s27
	v_mov_b32_e32 v86, v83
	v_bfe_u32 v74, v69, 16, 1
	v_add3_u32 v68, v68, v75, s27
	v_add3_u32 v9, v9, v73, s27
	v_lshrrev_b32_e32 v8, 16, v8
	v_pk_mul_f32 v[70:71], v[90:91], v[86:87]
	v_add3_u32 v69, v69, v74, s27
	v_lshrrev_b32_e32 v9, 16, v9
	v_and_or_b32 v68, v68, s42, v8
	v_add_u32_e32 v8, s45, v33
	v_bfe_u32 v74, v70, 16, 1
	v_bfe_u32 v75, v71, 16, 1
	v_and_or_b32 v69, v69, s42, v9
	v_ashrrev_i32_e32 v9, 31, v8
	v_add3_u32 v71, v71, v75, s27
	v_add3_u32 v70, v70, v74, s27
	v_lshlrev_b64 v[8:9], 13, v[8:9]
	v_lshrrev_b32_e32 v70, 16, v70
	v_lshrrev_b32_e32 v71, 16, v71
	v_lshl_add_u64 v[8:9], s[36:37], 0, v[8:9]
	v_and_or_b32 v71, v19, s42, v71
	v_and_or_b32 v70, v67, s42, v70
	v_lshl_add_u64 v[8:9], v[8:9], 0, v[12:13]
	ds_read2_b32 v[72:73], v31 offset0:16 offset1:24
	ds_read2_b32 v[74:75], v31 offset0:82 offset1:90
	global_store_dwordx4 v[8:9], v[68:71], off
	ds_read2_b32 v[8:9], v31 offset0:49 offset1:57
	ds_read2_b32 v[76:77], v31 offset0:115 offset1:123
	ds_read2_b32 v[78:79], v31 offset0:148 offset1:156
	ds_read2_b32 v[82:83], v31 offset0:214 offset1:222
	ds_read2_b32 v[84:85], v31 offset0:181 offset1:189
	ds_read2_b32 v[86:87], v31 offset0:247 offset1:255
	s_waitcnt lgkmcnt(7)
	v_mov_b32_e32 v68, v72
	s_waitcnt lgkmcnt(5)
	v_mov_b32_e32 v70, v8
	s_waitcnt lgkmcnt(3)
	v_mov_b32_e32 v88, v78
	s_waitcnt lgkmcnt(2)
	v_mov_b32_e32 v89, v82
	v_mov_b32_e32 v71, v76
	v_pk_mul_f32 v[88:89], v[90:91], v[88:89]
	v_mov_b32_e32 v69, v74
	v_pk_mul_f32 v[70:71], v[14:15], v[70:71]
	v_bfe_u32 v74, v88, 16, 1
	v_pk_mul_f32 v[68:69], v[80:81], v[68:69]
	s_waitcnt lgkmcnt(1)
	v_mov_b32_e32 v92, v84
	s_waitcnt lgkmcnt(0)
	v_mov_b32_e32 v93, v86
	v_bfe_u32 v67, v71, 16, 1
	v_bfe_u32 v72, v70, 16, 1
	v_bfe_u32 v76, v89, 16, 1
	v_add3_u32 v74, v88, v74, s27
	v_add_u32_e32 v88, s45, v34
	v_pk_mul_f32 v[92:93], v[10:11], v[92:93]
	v_add3_u32 v72, v70, v72, s27
	v_add3_u32 v67, v71, v67, s27
	v_bfe_u32 v70, v68, 16, 1
	v_bfe_u32 v71, v69, 16, 1
	v_add3_u32 v76, v89, v76, s27
	v_ashrrev_i32_e32 v89, 31, v88
	v_bfe_u32 v8, v93, 16, 1
	v_bfe_u32 v19, v92, 16, 1
	v_add3_u32 v69, v69, v71, s27
	v_add3_u32 v68, v68, v70, s27
	v_lshlrev_b64 v[88:89], 13, v[88:89]
	v_add3_u32 v19, v92, v19, s27
	v_add3_u32 v8, v93, v8, s27
	v_lshrrev_b32_e32 v68, 16, v68
	v_lshrrev_b32_e32 v69, 16, v69
	v_lshrrev_b32_e32 v70, 16, v74
	v_lshrrev_b32_e32 v71, 16, v76
	v_lshl_add_u64 v[88:89], s[36:37], 0, v[88:89]
	v_mov_b32_e32 v76, v9
	v_and_or_b32 v71, v8, s42, v71
	v_and_or_b32 v70, v19, s42, v70
	v_and_or_b32 v69, v67, s42, v69
	v_and_or_b32 v68, v72, s42, v68
	v_lshl_add_u64 v[88:89], v[88:89], 0, v[12:13]
	v_pk_mul_f32 v[8:9], v[14:15], v[76:77]
	v_mov_b32_e32 v82, v79
	global_store_dwordx4 v[88:89], v[68:71], off
	v_pk_mul_f32 v[14:15], v[90:91], v[82:83]
	v_mov_b32_e32 v86, v85
	v_bfe_u32 v70, v9, 16, 1
	v_pk_mul_f32 v[10:11], v[10:11], v[86:87]
	v_bfe_u32 v71, v8, 16, 1
	v_add3_u32 v9, v9, v70, s27
	v_bfe_u32 v70, v14, 16, 1
	v_bfe_u32 v67, v10, 16, 1
	v_add3_u32 v8, v8, v71, s27
	v_bfe_u32 v71, v15, 16, 1
	v_add3_u32 v14, v14, v70, s27
	v_mov_b32_e32 v74, v73
	v_bfe_u32 v19, v11, 16, 1
	v_add3_u32 v10, v10, v67, s27
	v_add3_u32 v15, v15, v71, s27
	v_lshrrev_b32_e32 v14, 16, v14
	v_pk_mul_f32 v[68:69], v[80:81], v[74:75]
	v_add3_u32 v11, v11, v19, s27
	v_lshrrev_b32_e32 v15, 16, v15
	v_and_or_b32 v10, v10, s42, v14
	v_add_u32_e32 v14, s45, v18
	v_bfe_u32 v19, v68, 16, 1
	v_bfe_u32 v67, v69, 16, 1
	v_and_or_b32 v11, v11, s42, v15
	v_ashrrev_i32_e32 v15, 31, v14
	v_add3_u32 v67, v69, v67, s27
	v_add3_u32 v19, v68, v19, s27
	v_lshlrev_b64 v[14:15], 13, v[14:15]
	v_lshrrev_b32_e32 v19, 16, v19
	v_lshrrev_b32_e32 v67, 16, v67
	v_lshl_add_u64 v[14:15], s[36:37], 0, v[14:15]
	v_and_or_b32 v9, v9, s42, v67
	v_and_or_b32 v8, v8, s42, v19
	v_lshl_add_u64 v[12:13], v[14:15], 0, v[12:13]
	global_store_dwordx4 v[12:13], v[8:11], off
	s_waitcnt lgkmcnt(0)

.LBB0_32:
	s_waitcnt vmcnt(5)
	v_add_u32_e32 v8, s18, v21
	v_ashrrev_i32_e32 v11, 31, v8
	v_mad_u64_u32 v[8:9], s[48:49], v8, s16, 0
	s_ashr_i32 s19, s18, 31
	v_mov_b32_e32 v10, v9
	s_lshl_b64 s[38:39], s[18:19], 2
	v_mad_u64_u32 v[10:11], s[48:49], v11, s16, v[10:11]
	s_add_u32 s38, s30, s38
	v_mov_b32_e32 v9, v10
	s_addc_u32 s39, s31, s39
	v_lshl_add_u64 v[8:9], v[8:9], 2, s[28:29]
	s_ashr_i32 s21, s20, 31
	v_lshl_add_u64 v[8:9], s[20:21], 2, v[8:9]
	v_lshl_add_u64 v[8:9], v[8:9], 0, v[16:17]
	s_lshl_b64 s[48:49], s[16:17], 3
	v_lshl_add_u64 v[10:11], v[8:9], 0, s[48:49]
	s_waitcnt vmcnt(4)
	v_lshl_add_u64 v[12:13], v[10:11], 0, s[48:49]
	v_lshl_add_u64 v[14:15], v[12:13], 0, s[48:49]
	v_lshl_add_u64 v[70:71], v[14:15], 0, s[48:49]
	v_lshl_add_u64 v[72:73], v[70:71], 0, s[48:49]
	v_lshl_add_u64 v[74:75], v[72:73], 0, s[48:49]
	global_load_dword v19, v[8:9], off nt
	global_load_dword v67, v[10:11], off nt
	global_load_dword v68, v[12:13], off nt
	global_load_dword v69, v[14:15], off nt
	s_nop 0
	global_load_dword v70, v[70:71], off nt
	s_nop 0
	global_load_dword v71, v[72:73], off nt
	s_nop 0
	global_load_dword v72, v[74:75], off nt
	v_lshl_add_u64 v[8:9], v[74:75], 0, s[48:49]
	global_load_dword v73, v[8:9], off nt
	v_lshl_add_u64 v[8:9], v[8:9], 0, s[48:49]
	global_load_dword v74, v[8:9], off nt
	v_lshl_add_u64 v[8:9], v[8:9], 0, s[48:49]
	global_load_dword v75, v[8:9], off nt
	v_lshl_add_u64 v[8:9], v[8:9], 0, s[48:49]
	global_load_dword v76, v[8:9], off nt
	v_lshl_add_u64 v[8:9], v[8:9], 0, s[48:49]
	global_load_dword v77, v[8:9], off nt
	v_lshl_add_u64 v[8:9], v[8:9], 0, s[48:49]
	global_load_dword v78, v[8:9], off nt
	v_lshl_add_u64 v[8:9], v[8:9], 0, s[48:49]
	global_load_dword v79, v[8:9], off nt
	v_lshl_add_u64 v[8:9], v[8:9], 0, s[48:49]
	global_load_dword v80, v[8:9], off nt
	v_lshl_add_u64 v[8:9], v[8:9], 0, s[48:49]
	global_load_dword v81, v[8:9], off nt
	v_lshl_add_u64 v[8:9], v[8:9], 0, s[48:49]
	global_load_dword v82, v[8:9], off nt
	v_lshl_add_u64 v[8:9], v[8:9], 0, s[48:49]
	global_load_dword v83, v[8:9], off nt
	v_lshl_add_u64 v[8:9], v[8:9], 0, s[48:49]
	global_load_dword v84, v[8:9], off nt
	v_lshl_add_u64 v[8:9], v[8:9], 0, s[48:49]
	global_load_dword v85, v[8:9], off nt
	v_lshl_add_u64 v[8:9], v[8:9], 0, s[48:49]
	global_load_dword v86, v[8:9], off nt
	v_lshl_add_u64 v[8:9], v[8:9], 0, s[48:49]
	global_load_dword v87, v[8:9], off nt
	v_lshl_add_u64 v[8:9], v[8:9], 0, s[48:49]
	global_load_dword v88, v[8:9], off nt
	v_lshl_add_u64 v[8:9], v[8:9], 0, s[48:49]
	global_load_dword v89, v[8:9], off nt
	v_lshl_add_u64 v[8:9], v[8:9], 0, s[48:49]
	global_load_dword v90, v[8:9], off nt
	v_lshl_add_u64 v[8:9], v[8:9], 0, s[48:49]
	global_load_dword v91, v[8:9], off nt
	v_lshl_add_u64 v[8:9], v[8:9], 0, s[48:49]
	global_load_dword v92, v[8:9], off nt
	v_lshl_add_u64 v[8:9], v[8:9], 0, s[48:49]
	global_load_dword v93, v[8:9], off nt
	v_lshl_add_u64 v[8:9], v[8:9], 0, s[48:49]
	global_load_dword v94, v[8:9], off nt
	v_lshl_add_u64 v[8:9], v[8:9], 0, s[48:49]
	global_load_dword v95, v[8:9], off nt
	v_lshl_add_u64 v[8:9], v[8:9], 0, s[48:49]
	global_load_dword v96, v[8:9], off nt
	v_lshl_add_u64 v[8:9], v[8:9], 0, s[48:49]
	global_load_dword v97, v[8:9], off nt
	s_waitcnt vmcnt(62)
	ds_write2_b32 v22, v35, v36 offset1:66
	ds_write2_b32 v22, v37, v39 offset0:132 offset1:198
	ds_write2_b32 v23, v40, v41 offset0:8 offset1:74
	global_load_dwordx4 v[8:11], v20, s[38:39] offset:16
	global_load_dwordx4 v[12:15], v20, s[38:39]
	ds_write2_b32 v23, v38, v42 offset0:140 offset1:206
	s_waitcnt vmcnt(62)
	ds_write2_b32 v24, v43, v44 offset0:16 offset1:82
	s_waitcnt vmcnt(60)
	ds_write2_b32 v24, v45, v46 offset0:148 offset1:214
	s_waitcnt vmcnt(58)
	ds_write2_b32 v25, v47, v48 offset0:24 offset1:90
	s_waitcnt vmcnt(56)
	ds_write2_b32 v25, v49, v50 offset0:156 offset1:222
	s_waitcnt vmcnt(54)
	ds_write2_b32 v26, v51, v52 offset0:32 offset1:98
	s_waitcnt vmcnt(52)
	ds_write2_b32 v26, v53, v54 offset0:164 offset1:230
	s_waitcnt vmcnt(50)
	ds_write2_b32 v27, v55, v56 offset0:40 offset1:106
	s_waitcnt vmcnt(48)
	ds_write2_b32 v27, v57, v58 offset0:172 offset1:238
	s_waitcnt vmcnt(45)
	ds_write2_b32 v28, v59, v60 offset0:48 offset1:114
	s_waitcnt vmcnt(44)
	ds_write2_b32 v28, v61, v62 offset0:180 offset1:246
	s_waitcnt vmcnt(41)
	ds_write2_b32 v29, v63, v64 offset0:56 offset1:122
	s_waitcnt vmcnt(40)
	ds_write2_b32 v29, v65, v66 offset0:188 offset1:254
	s_waitcnt lgkmcnt(0)
	ds_read2_b32 v[40:41], v31 offset0:33 offset1:41
	ds_read2_b32 v[42:43], v31 offset0:99 offset1:107
	ds_read2_b32 v[46:47], v31 offset1:8
	ds_read2_b32 v[48:49], v31 offset0:132 offset1:140
	ds_read2_b32 v[50:51], v31 offset0:165 offset1:173
	ds_read2_b32 v[52:53], v31 offset0:198 offset1:206
	ds_read2_b32 v[54:55], v31 offset0:231 offset1:239
	s_waitcnt vmcnt(38)
	v_mov_b32_e32 v45, v6
	v_mov_b32_e32 v6, v5
	s_waitcnt lgkmcnt(6)
	v_mov_b32_e32 v36, v40
	s_waitcnt lgkmcnt(5)
	v_mov_b32_e32 v37, v42
	v_pk_mul_f32 v[36:37], v[6:7], v[36:37]
	v_mov_b32_e32 v56, v0
	v_mov_b32_e32 v57, v2
	v_mov_b32_e32 v2, v1
	s_waitcnt lgkmcnt(2)
	v_mov_b32_e32 v0, v50
	s_waitcnt lgkmcnt(0)
	v_mov_b32_e32 v1, v54
	v_pk_mul_f32 v[0:1], v[2:3], v[0:1]
	v_bfe_u32 v5, v37, 16, 1
	v_bfe_u32 v35, v36, 16, 1
	v_add3_u32 v35, v36, v35, s27
	v_add3_u32 v36, v37, v5, s27
	v_bfe_u32 v5, v1, 16, 1
	v_bfe_u32 v37, v0, 16, 1
	v_add3_u32 v37, v0, v37, s27
	v_add3_u32 v40, v1, v5, s27
	ds_read2_b32 v[0:1], v31 offset0:66 offset1:74
	v_mov_b32_e32 v38, v48
	v_mov_b32_e32 v39, v52
	v_pk_mul_f32 v[38:39], v[56:57], v[38:39]
	v_mov_b32_e32 v44, v4
	v_bfe_u32 v5, v38, 16, 1
	v_add3_u32 v38, v38, v5, s27
	v_mov_b32_e32 v4, v46
	s_waitcnt lgkmcnt(0)
	v_mov_b32_e32 v5, v0
	v_pk_mul_f32 v[4:5], v[44:45], v[4:5]
	v_bfe_u32 v42, v39, 16, 1
	v_bfe_u32 v0, v5, 16, 1
	v_add3_u32 v39, v39, v42, s27
	v_add3_u32 v0, v5, v0, s27
	v_bfe_u32 v5, v4, 16, 1
	v_add3_u32 v4, v4, v5, s27
	v_lshrrev_b32_e32 v5, 16, v38
	v_lshrrev_b32_e32 v38, 16, v39
	v_lshrrev_b32_e32 v0, 16, v0
	v_and_or_b32 v39, v40, s42, v38
	v_and_or_b32 v38, v37, s42, v5
	v_and_or_b32 v37, v36, s42, v0
	v_lshrrev_b32_e32 v0, 16, v4
	v_add_u32_e32 v4, s26, v30
	v_ashrrev_i32_e32 v5, 31, v4
	v_add_u32_e32 v58, s44, v32
	v_lshlrev_b64 v[4:5], 13, v[4:5]
	v_ashrrev_i32_e32 v59, 31, v58
	v_lshl_add_u64 v[4:5], s[34:35], 0, v[4:5]
	v_lshlrev_b64 v[58:59], 1, v[58:59]
	v_and_or_b32 v36, v35, s42, v0
	v_lshl_add_u64 v[4:5], v[4:5], 0, v[58:59]
	v_mov_b32_e32 v42, v41
	v_mov_b32_e32 v54, v51
	global_store_dwordx4 v[4:5], v[36:39], off
	v_mov_b32_e32 v0, v47
	v_pk_mul_f32 v[4:5], v[6:7], v[42:43]
	v_mov_b32_e32 v52, v49
	v_pk_mul_f32 v[38:39], v[2:3], v[54:55]
	v_pk_mul_f32 v[0:1], v[44:45], v[0:1]
	v_pk_mul_f32 v[36:37], v[56:57], v[52:53]
	v_bfe_u32 v35, v39, 16, 1
	v_bfe_u32 v41, v5, 16, 1
	v_bfe_u32 v40, v38, 16, 1
	v_bfe_u32 v42, v4, 16, 1
	v_add3_u32 v5, v5, v41, s27
	v_add3_u32 v35, v39, v35, s27
	v_bfe_u32 v39, v0, 16, 1
	v_bfe_u32 v41, v36, 16, 1
	v_add3_u32 v4, v4, v42, s27
	v_add3_u32 v38, v38, v40, s27
	v_bfe_u32 v40, v1, 16, 1
	v_bfe_u32 v42, v37, 16, 1
	v_add3_u32 v36, v36, v41, s27
	v_add3_u32 v0, v0, v39, s27
	v_add3_u32 v37, v37, v42, s27
	v_add3_u32 v1, v1, v40, s27
	v_lshrrev_b32_e32 v0, 16, v0
	v_lshrrev_b32_e32 v36, 16, v36
	v_lshrrev_b32_e32 v1, 16, v1
	v_lshrrev_b32_e32 v37, 16, v37
	v_and_or_b32 v38, v38, s42, v36
	v_and_or_b32 v36, v4, s42, v0
	v_add_u32_e32 v0, s26, v33
	v_and_or_b32 v39, v35, s42, v37
	v_and_or_b32 v37, v5, s42, v1
	v_ashrrev_i32_e32 v1, 31, v0
	v_lshlrev_b64 v[0:1], 13, v[0:1]
	v_lshl_add_u64 v[0:1], s[34:35], 0, v[0:1]
	v_lshl_add_u64 v[0:1], v[0:1], 0, v[58:59]
	ds_read2_b32 v[4:5], v31 offset0:49 offset1:57
	ds_read2_b32 v[40:41], v31 offset0:115 offset1:123
	global_store_dwordx4 v[0:1], v[36:39], off
	ds_read2_b32 v[42:43], v31 offset0:148 offset1:156
	ds_read2_b32 v[46:47], v31 offset0:214 offset1:222
	ds_read2_b32 v[48:49], v31 offset0:181 offset1:189
	ds_read2_b32 v[50:51], v31 offset0:247 offset1:255
	s_waitcnt lgkmcnt(5)
	v_mov_b32_e32 v0, v4
	s_waitcnt lgkmcnt(4)
	v_mov_b32_e32 v1, v40
	v_pk_mul_f32 v[0:1], v[6:7], v[0:1]
	s_waitcnt lgkmcnt(1)
	v_mov_b32_e32 v38, v48
	s_waitcnt lgkmcnt(0)
	v_mov_b32_e32 v39, v50
	v_pk_mul_f32 v[38:39], v[2:3], v[38:39]
	v_bfe_u32 v4, v1, 16, 1
	v_bfe_u32 v35, v0, 16, 1
	v_add3_u32 v35, v0, v35, s27
	v_add3_u32 v4, v1, v4, s27
	v_bfe_u32 v0, v39, 16, 1
	v_bfe_u32 v1, v38, 16, 1
	v_add3_u32 v38, v38, v1, s27
	v_add3_u32 v39, v39, v0, s27
	ds_read2_b32 v[0:1], v31 offset0:16 offset1:24
	ds_read2_b32 v[52:53], v31 offset0:82 offset1:90
	v_mov_b32_e32 v36, v42
	v_mov_b32_e32 v37, v46
	v_pk_mul_f32 v[36:37], v[56:57], v[36:37]
	v_add_u32_e32 v54, s26, v34
	v_bfe_u32 v40, v36, 16, 1
	v_bfe_u32 v42, v37, 16, 1
	v_add3_u32 v42, v37, v42, s27
	v_add3_u32 v40, v36, v40, s27
	s_waitcnt lgkmcnt(1)
	v_mov_b32_e32 v36, v0
	s_waitcnt lgkmcnt(0)
	v_mov_b32_e32 v37, v52
	v_pk_mul_f32 v[36:37], v[44:45], v[36:37]
	v_ashrrev_i32_e32 v55, 31, v54
	v_bfe_u32 v0, v37, 16, 1
	v_add3_u32 v0, v37, v0, s27
	v_bfe_u32 v37, v36, 16, 1
	v_add3_u32 v36, v36, v37, s27
	v_lshrrev_b32_e32 v37, 16, v40
	v_lshrrev_b32_e32 v0, 16, v0
	v_lshlrev_b64 v[54:55], 13, v[54:55]
	v_mov_b32_e32 v50, v49
	v_lshrrev_b32_e32 v40, 16, v42
	v_and_or_b32 v38, v38, s42, v37
	v_and_or_b32 v37, v4, s42, v0
	v_lshrrev_b32_e32 v0, 16, v36
	v_lshl_add_u64 v[54:55], s[34:35], 0, v[54:55]
	v_mov_b32_e32 v52, v1
	v_pk_mul_f32 v[2:3], v[2:3], v[50:51]
	v_and_or_b32 v39, v39, s42, v40
	v_and_or_b32 v36, v35, s42, v0
	v_lshl_add_u64 v[54:55], v[54:55], 0, v[58:59]
	v_pk_mul_f32 v[0:1], v[44:45], v[52:53]
	v_mov_b32_e32 v40, v5
	v_bfe_u32 v35, v3, 16, 1
	global_store_dwordx4 v[54:55], v[36:39], off
	v_pk_mul_f32 v[4:5], v[6:7], v[40:41]
	v_add3_u32 v3, v3, v35, s27
	v_bfe_u32 v36, v2, 16, 1
	v_bfe_u32 v35, v0, 16, 1
	v_bfe_u32 v38, v4, 16, 1
	v_add3_u32 v2, v2, v36, s27
	v_bfe_u32 v36, v1, 16, 1
	v_add3_u32 v0, v0, v35, s27
	v_mov_b32_e32 v46, v43
	v_bfe_u32 v37, v5, 16, 1
	v_add3_u32 v4, v4, v38, s27
	v_add3_u32 v1, v1, v36, s27
	v_lshrrev_b32_e32 v0, 16, v0
	v_pk_mul_f32 v[6:7], v[56:57], v[46:47]
	v_add3_u32 v5, v5, v37, s27
	v_lshrrev_b32_e32 v1, 16, v1
	v_and_or_b32 v0, v4, s42, v0
	v_add_u32_e32 v4, s26, v18
	v_bfe_u32 v37, v6, 16, 1
	v_bfe_u32 v38, v7, 16, 1
	v_and_or_b32 v1, v5, s42, v1
	v_ashrrev_i32_e32 v5, 31, v4
	v_add3_u32 v7, v7, v38, s27
	v_add3_u32 v6, v6, v37, s27
	v_lshlrev_b64 v[4:5], 13, v[4:5]
	v_lshrrev_b32_e32 v6, 16, v6
	v_lshrrev_b32_e32 v7, 16, v7
	v_lshl_add_u64 v[4:5], s[34:35], 0, v[4:5]
	v_and_or_b32 v3, v3, s42, v7
	v_and_or_b32 v2, v2, s42, v6
	v_lshl_add_u64 v[4:5], v[4:5], 0, v[58:59]
	global_store_dwordx4 v[4:5], v[0:3], off
	s_waitcnt lgkmcnt(0)
	s_andn2_b64 vcc, exec, s[40:41]
	s_mov_b64 s[38:39], -1
	s_cbranch_vccnz .LBB0_25
	s_and_b64 s[34:35], s[40:41], exec
	s_cselect_b32 s19, s33, 0
	s_add_i32 s19, s19, s43
	s_cmp_lt_i32 s19, 0x10200
	s_cselect_b64 s[40:41], -1, 0
	s_cmp_gt_i32 s19, 0x101ff
	s_cselect_b64 s[38:39], -1, 0
	s_and_b64 vcc, exec, s[38:39]
	s_mov_b32 s44, s46
	s_mov_b32 s26, s45
	s_mov_b64 s[34:35], s[36:37]
	s_cbranch_vccnz .LBB0_24
	s_cmp_gt_i32 s19, 0xabff
	s_mov_b64 s[28:29], -1
	s_cbranch_scc0 .LBB0_36
	s_add_i32 s0, s19, 0xffff5400
	s_lshr_b32 s16, s0, 13
	s_lshl_b64 s[20:21], s[16:17], 25
	s_add_u32 s34, s23, s20
	s_addc_u32 s35, s25, s21
	s_lshr_b32 s0, s0, 1
	s_lshl_b32 s1, s19, 5
	s_and_b32 s18, s0, 0x7fffffc0
	s_and_b32 s20, s1, 0xfe0
	s_and_b32 s44, s0, 0xfc0
	s_mov_b64 s[28:29], 0
